# P1 idle-tail weight copies rebalanced too (W_in pass 2 / W_uq / W_ukv items start at waves 448 / 600 / 750 of the copy team) on top of the P3 rebalance
# baseline (speedup 1.0000x reference)
; #define LAS __attribute__((address_space(3)))
;     if (nb1 < 0) nb1 = N / 32;
;     const int nblk = nb1 - nb0, nitems = (K / 64) * nblk;
;     for (int item = gw; item < nitems; item += ngw) {
;         const int kb = item / nblk, nb = nb0 + item % nblk, k0 = 64 * kb, n0 = 32 * nb;
; __global__ void __launch_bounds__(512, 2) fwd_mega(Args args) {
;     ...
;             LAS float* scr = (LAS float*)(lds + wave * 16384); const int gw2 = (bx - 136) * 8 + wave, ngw2 = 120 * 8;
;             transpose_mat(args.in[5], 2816, 1024, nullptr, 0, wDN1, nullptr, scr, gw2, ngw2, lane);
;             transpose_mat(args.in[7], 1024, 5280, args.in[6], 2, wIN, wGT, scr, gw2, ngw2, lane, 0, 69);
.LBB0_349:
	v_or_b32_e32 v1, 2, v0
	v_mov_b32_e32 v3, 0x108
	v_mad_u32_u24 v52, v1, s8, v3
	v_mov_b32_e32 v3, 0x318
	v_mad_u32_u24 v53, v1, s8, v3
	v_mov_b32_e32 v3, 0x528
	v_mad_u32_u24 v37, v1, s8, v3
	v_mov_b32_e32 v3, 0x738
	v_mad_u32_u24 v38, v1, s8, v3
	v_mov_b32_e32 v3, 0x948
	v_mad_u32_u24 v39, v1, s8, v3
	v_mov_b32_e32 v3, 0xb58
	v_mad_u32_u24 v40, v1, s8, v3
	v_mov_b32_e32 v3, 0xd68
	v_mad_u32_u24 v41, v1, s8, v3
	v_mov_b32_e32 v3, 0xf78
	v_mad_u32_u24 v42, v1, s8, v3
	v_mov_b32_e32 v3, 0x1188
	v_mad_u32_u24 v43, v1, s8, v3
	v_mov_b32_e32 v3, 0x1398
	v_mad_u32_u24 v44, v1, s8, v3
	v_mov_b32_e32 v3, 0x15a8
	v_mad_u32_u24 v45, v1, s8, v3
	v_mov_b32_e32 v3, 0x17b8
	v_or_b32_e32 v50, 8, v47
	v_or_b32_e32 v49, 16, v47
	v_or_b32_e32 v48, 24, v47
	s_add_i32 s100, s33, 0xfffffe40
	s_cmp_lt_i32 s100, 0
	s_cselect_b32 s101, 0x3c0, 0
	s_add_i32 s100, s100, s101
	s_nop 0
	s_nop 0
	s_cmpk_gt_i32 s100, 0x44f
	v_mul_u32_u24_e32 v51, 0x84, v1
	v_mad_u32_u24 v46, v1, s8, v3
	s_cbranch_scc1 .LBB0_397
	s_add_u32 s34, s4, 0x1080000
	s_mov_b32 s44, s72
	s_addc_u32 s35, s5, 0
	v_readlane_b32 s68, v249, 17
	s_add_u32 s36, s4, 0x1500000
	v_readlane_b32 s80, v249, 29
	v_readlane_b32 s81, v249, 30
	s_addc_u32 s37, s5, 0
	v_mov_b32_e32 v3, 0
	v_readlane_b32 s82, v249, 31
	v_readlane_b32 s83, v249, 32
	s_mov_b64 s[48:49], s[80:81]
	v_mov_b32_e32 v5, v3
	s_mov_b64 s[50:51], s[82:83]
	s_cmp_lg_u64 s[48:49], 0
	v_lshlrev_b32_e32 v8, 10, v47
	v_lshlrev_b32_e32 v10, 10, v50
	v_lshlrev_b32_e32 v12, 10, v49
	v_lshlrev_b32_e32 v14, 10, v48
	v_lshl_add_u64 v[6:7], s[50:51], 0, v[4:5]
	s_cselect_b64 s[6:7], -1, 0
	v_mov_b32_e32 v1, v3
	s_lshl_b32 s38, s100, 5
	s_lshl_b32 s39, s100, 15
	s_movk_i32 s40, 0x5280
	s_mov_b32 s9, 0
	v_lshlrev_b32_e32 v8, 1, v8
	v_lshlrev_b32_e32 v10, 1, v10
	v_lshlrev_b32_e32 v12, 1, v12
	v_lshlrev_b32_e32 v14, 1, v14
	s_mov_b32 s41, s100
	v_readlane_b32 s69, v249, 18
	v_readlane_b32 s70, v249, 19
	v_readlane_b32 s71, v249, 20
	v_readlane_b32 s72, v249, 21
	v_readlane_b32 s73, v249, 22
	v_readlane_b32 s74, v249, 23
	v_readlane_b32 s75, v249, 24
	v_readlane_b32 s76, v249, 25
	v_readlane_b32 s77, v249, 26
	v_readlane_b32 s78, v249, 27
	v_readlane_b32 s79, v249, 28
	s_branch .LBB0_352

;     ...
;     const int nblk = nb1 - nb0, nitems = (K / 64) * nblk;
;     for (int item = gw; item < nitems; item += ngw) {
;         const int kb = item / nblk, nb = nb0 + item % nblk, k0 = 64 * kb, n0 = 32 * nb;
; __global__ void __launch_bounds__(512, 2) fwd_mega(Args args) {
;     ...
;             transpose_mat(args.in[14], 384, 768, args.in[13], 0, wUQ, nullptr, scr, gw2, ngw2, lane);
.LBB0_397:
	s_add_i32 s100, s33, 0xfffffda8
	s_cmp_lt_i32 s100, 0
	s_cselect_b32 s101, 0x3c0, 0
	s_add_i32 s100, s100, s101
	s_nop 0
	s_nop 0
	s_cmpk_gt_i32 s100, 0x8f
	v_add_u32_e32 v32, v34, v51
	v_add_u32_e32 v33, v34, v52
	v_add_u32_e32 v51, v34, v53
	s_cbranch_scc1 .LBB0_432
	s_add_u32 s12, s4, 0x1b80000
	v_readlane_b32 s36, v249, 33
	s_addc_u32 s13, s5, 0
	v_readlane_b32 s46, v249, 43
	v_readlane_b32 s47, v249, 44
	v_mov_b32_e32 v3, 0
	s_cmp_lg_u64 s[46:47], 0
	v_mov_b32_e32 v5, v3
	v_readlane_b32 s48, v249, 45
	v_readlane_b32 s49, v249, 46
	s_cselect_b64 s[2:3], -1, 0
	v_mul_u32_u24_e32 v8, 0x180, v47
	v_lshl_add_u64 v[6:7], s[48:49], 0, v[4:5]
	v_cndmask_b32_e64 v5, 0, 1, s[2:3]
	v_mov_b32_e32 v1, v3
	s_lshl_b32 s14, s100, 5
	s_movk_i32 s15, 0xc00
	v_cmp_ne_u32_e64 s[2:3], 1, v5
	v_lshlrev_b32_e32 v8, 1, v8
	s_movk_i32 s34, 0x1000
	s_movk_i32 s35, 0x3000
	s_mov_b32 s36, s100
	v_readlane_b32 s37, v249, 34
	v_readlane_b32 s38, v249, 35
	v_readlane_b32 s39, v249, 36
	v_readlane_b32 s40, v249, 37
	v_readlane_b32 s41, v249, 38
	v_readlane_b32 s42, v249, 39
	v_readlane_b32 s43, v249, 40
	v_readlane_b32 s44, v249, 41
	v_readlane_b32 s45, v249, 42
	v_readlane_b32 s50, v249, 47
	v_readlane_b32 s51, v249, 48
	s_branch .LBB0_400

;     ...
;     const int nblk = nb1 - nb0, nitems = (K / 64) * nblk;
;     for (int item = gw; item < nitems; item += ngw) {
;         const int kb = item / nblk, nb = nb0 + item % nblk, k0 = 64 * kb, n0 = 32 * nb;
; __global__ void __launch_bounds__(512, 2) fwd_mega(Args args) {
;     ...
;             transpose_mat(args.in[16], 256, 1024, args.in[15], 0, wUKV, nullptr, scr, gw2, ngw2, lane);
.LBB0_432:
	s_add_i32 s33, s33, 0xfffffd12
	s_cmp_lt_i32 s33, 0
	s_cselect_b32 s101, 0x3c0, 0
	s_add_i32 s33, s33, s101
	s_nop 0
	s_nop 0
	s_cmpk_gt_i32 s33, 0x7f
	s_cbranch_scc1 .LBB0_467
	s_add_u32 s10, s4, 0x1c80000
	v_readlane_b32 s36, v249, 33
	s_addc_u32 s11, s5, 0
	v_readlane_b32 s50, v249, 47
	v_readlane_b32 s51, v249, 48
	s_cmp_lg_u64 s[50:51], 0
	v_mov_b32_e32 v3, 0
	s_cselect_b64 s[2:3], -1, 0
	v_mov_b32_e32 v5, v3
	v_lshlrev_b32_e32 v6, 8, v47
	v_lshlrev_b32_e32 v8, 8, v50
	v_lshlrev_b32_e32 v10, 8, v49
	v_lshlrev_b32_e32 v12, 8, v48
	v_cndmask_b32_e64 v7, 0, 1, s[2:3]
	v_lshl_add_u64 v[4:5], s[52:53], 0, v[4:5]
	v_mov_b32_e32 v1, v3
	s_lshl_b32 s12, s33, 5
	v_cmp_ne_u32_e64 s[2:3], 1, v7
	v_lshlrev_b32_e32 v6, 1, v6
	v_lshlrev_b32_e32 v8, 1, v8
	v_lshlrev_b32_e32 v10, 1, v10
	v_lshlrev_b32_e32 v12, 1, v12
	v_readlane_b32 s37, v249, 34
	v_readlane_b32 s38, v249, 35
	v_readlane_b32 s39, v249, 36
	v_readlane_b32 s40, v249, 37
	v_readlane_b32 s41, v249, 38
	v_readlane_b32 s42, v249, 39
	v_readlane_b32 s43, v249, 40
	v_readlane_b32 s44, v249, 41
	v_readlane_b32 s45, v249, 42
	v_readlane_b32 s46, v249, 43
	v_readlane_b32 s47, v249, 44
	v_readlane_b32 s48, v249, 45
	v_readlane_b32 s49, v249, 46
	s_branch .LBB0_435
